# v46 + slot-0 scalar bookkeeping interleaved between the exp fillers (SALU issued while the transcendental unit is busy)
# baseline (speedup 1.0000x reference)
.Latt_loop:
	s_waitcnt lgkmcnt(5)
	v_mfma_f32_32x32x16_bf16 v[98:113], v[238:241], v[134:137], 0
	v_exp_f32_e32 v66, v66
	s_add_i32 s13, s12, 1
	s_cmp_eq_u32 s12, 2
	s_cselect_b32 s12, 0, s13
	v_exp_f32_e32 v67, v67
	s_mul_i32 s15, s12, 0x4800
	s_mul_i32 s16, s12, 0x6000
	s_add_i32 s16, s16, 0xd800
	v_exp_f32_e32 v68, v68
	s_add_i32 s17, s14, 2
	s_min_u32 s17, s17, s11
	s_lshl_b32 s64, s17, 17
	s_add_u32 s18, s64, s83
	s_mov_b32 s19, 0
	s_add_i32 s14, s14, 1
	v_mfma_f32_32x32x16_bf16 v[34:49], v[182:185], v[118:121], v[34:49]
	v_exp_f32_e32 v69, v69
	v_exp_f32_e32 v70, v70
	v_exp_f32_e32 v71, v71
	v_mov_b32_e32 v250, v251
	v_add3_u32 v251, s15, v236, v210
	v_mov_b32_e32 v252, v215
	v_add_u32_e32 v215, s16, v232
	ds_read_b128 v[238:241], v250 offset:4672
	ds_read_b64_tr_b16 v[182:183], v252 offset:3072
	ds_read_b64_tr_b16 v[184:185], v252 offset:4608
	v_mfma_f32_32x32x16_bf16 v[50:65], v[186:189], v[118:121], v[50:65]
	v_exp_f32_e32 v72, v72
	v_exp_f32_e32 v73, v73
	v_cvt_pk_bf16_f32 v66, v66, v67
	v_cvt_pk_bf16_f32 v67, v68, v69
	ds_read_b64_tr_b16 v[186:187], v252 offset:3136
	ds_read_b64_tr_b16 v[188:189], v252 offset:4672
	v_mfma_f32_16x16x32_bf16 v[170:173], v[130:133], v[118:121], v[170:173]
	v_cvt_pk_bf16_f32 v68, v70, v71
	v_cvt_pk_bf16_f32 v69, v72, v73
	s_waitcnt lgkmcnt(5)
	v_mfma_f32_32x32x16_bf16 v[98:113], v[242:245], v[138:141], v[98:113]
	v_exp_f32_e32 v82, v82
	v_exp_f32_e32 v83, v83
	v_exp_f32_e32 v84, v84
	ds_read_b128 v[242:245], v250 offset:4704
	s_waitcnt vmcnt(0)
	v_add_u32_e32 v246, s15, v204
	v_add_u32_e32 v247, s16, v231
	ds_write_b128 v246, v[158:161]
	ds_write_b128 v246, v[162:165] offset:9216
	v_mfma_f32_32x32x16_bf16 v[2:17], v[174:177], v[66:69], v[2:17]
	v_exp_f32_e32 v85, v85
	v_exp_f32_e32 v86, v86
	v_exp_f32_e32 v87, v87
	ds_write_b128 v247, v[150:153]
	ds_write_b128 v247, v[154:157] offset:12288
	v_mfma_f32_32x32x16_bf16 v[18:33], v[178:181], v[66:69], v[18:33]
	v_exp_f32_e32 v88, v88
	v_exp_f32_e32 v89, v89
	v_cvt_pk_bf16_f32 v82, v82, v83
	v_cvt_pk_bf16_f32 v83, v84, v85
	s_add_u32 s18, s100, s64
	s_addc_u32 s19, s101, 0
	global_load_dwordx4 v[158:161], v248, s[18:19]
	global_load_dwordx4 v[162:165], v249, s[18:19]
	v_mfma_f32_16x16x32_bf16 v[166:169], v[130:133], v[66:69], v[166:169]
	v_cvt_pk_bf16_f32 v84, v86, v87
	v_cvt_pk_bf16_f32 v85, v88, v89
	s_waitcnt lgkmcnt(9)
	v_mfma_f32_32x32x16_bf16 v[114:129], v[238:241], v[142:145], 0
	v_exp_f32_e32 v74, v74
	v_exp_f32_e32 v75, v75
	v_exp_f32_e32 v76, v76
	ds_read_b128 v[238:241], v250 offset:9216
	v_mfma_f32_32x32x16_bf16 v[34:49], v[174:177], v[82:85], v[34:49]
	v_exp_f32_e32 v77, v77
	v_exp_f32_e32 v78, v78
	v_exp_f32_e32 v79, v79
	ds_read_b64_tr_b16 v[174:175], v252 offset:6144
	ds_read_b64_tr_b16 v[176:177], v252 offset:7680
	v_mfma_f32_32x32x16_bf16 v[50:65], v[178:181], v[82:85], v[50:65]
	v_exp_f32_e32 v80, v80
	v_exp_f32_e32 v81, v81
	v_cvt_pk_bf16_f32 v70, v74, v75
	v_cvt_pk_bf16_f32 v71, v76, v77
	ds_read_b64_tr_b16 v[178:179], v252 offset:6208
	ds_read_b64_tr_b16 v[180:181], v252 offset:7744
	v_mfma_f32_16x16x32_bf16 v[170:173], v[130:133], v[82:85], v[170:173]
	v_cvt_pk_bf16_f32 v72, v78, v79
	v_cvt_pk_bf16_f32 v73, v80, v81
	s_waitcnt lgkmcnt(9)
	v_mfma_f32_32x32x16_bf16 v[114:129], v[242:245], v[146:149], v[114:129]
	v_exp_f32_e32 v90, v90
	v_exp_f32_e32 v91, v91
	v_exp_f32_e32 v92, v92
	ds_read_b128 v[242:245], v250 offset:9248
	v_mfma_f32_32x32x16_bf16 v[2:17], v[182:185], v[70:73], v[2:17]
	v_exp_f32_e32 v93, v93
	v_exp_f32_e32 v94, v94
	v_exp_f32_e32 v95, v95
	s_add_u32 s18, s18, 0x1040000
	s_addc_u32 s19, s19, 0
	global_load_dwordx4 v[150:153], v248, s[18:19]
	global_load_dwordx4 v[154:157], v249, s[18:19]
	v_mfma_f32_32x32x16_bf16 v[18:33], v[186:189], v[70:73], v[18:33]
	v_exp_f32_e32 v96, v96
	v_exp_f32_e32 v97, v97
	v_cvt_pk_bf16_f32 v86, v90, v91
	v_cvt_pk_bf16_f32 v87, v92, v93
	v_mfma_f32_16x16x32_bf16 v[166:169], v[130:133], v[70:73], v[166:169]
	v_cvt_pk_bf16_f32 v88, v94, v95
	v_cvt_pk_bf16_f32 v89, v96, v97
	s_waitcnt lgkmcnt(5)
	v_mfma_f32_32x32x16_bf16 v[66:81], v[238:241], v[134:137], 0
	v_exp_f32_e32 v98, v98
	v_exp_f32_e32 v99, v99
	v_exp_f32_e32 v100, v100
	ds_read_b128 v[238:241], v250 offset:9280
	v_mfma_f32_32x32x16_bf16 v[34:49], v[182:185], v[86:89], v[34:49]
	v_exp_f32_e32 v101, v101
	v_exp_f32_e32 v102, v102
	v_exp_f32_e32 v103, v103
	ds_read_b64_tr_b16 v[182:183], v252 offset:9216
	ds_read_b64_tr_b16 v[184:185], v252 offset:10752
	v_mfma_f32_32x32x16_bf16 v[50:65], v[186:189], v[86:89], v[50:65]
	v_exp_f32_e32 v104, v104
	v_exp_f32_e32 v105, v105
	v_cvt_pk_bf16_f32 v98, v98, v99
	v_cvt_pk_bf16_f32 v99, v100, v101
	ds_read_b64_tr_b16 v[186:187], v252 offset:9280
	ds_read_b64_tr_b16 v[188:189], v252 offset:10816
	v_mfma_f32_16x16x32_bf16 v[170:173], v[130:133], v[86:89], v[170:173]
	v_cvt_pk_bf16_f32 v100, v102, v103
	v_cvt_pk_bf16_f32 v101, v104, v105
	s_waitcnt lgkmcnt(5)
	v_mfma_f32_32x32x16_bf16 v[66:81], v[242:245], v[138:141], v[66:81]
	v_exp_f32_e32 v114, v114
	v_exp_f32_e32 v115, v115
	v_exp_f32_e32 v116, v116
	ds_read_b128 v[242:245], v250 offset:9312
	v_mfma_f32_32x32x16_bf16 v[2:17], v[174:177], v[98:101], v[2:17]
	v_exp_f32_e32 v117, v117
	v_exp_f32_e32 v118, v118
	v_exp_f32_e32 v119, v119
	v_mfma_f32_32x32x16_bf16 v[18:33], v[178:181], v[98:101], v[18:33]
	v_exp_f32_e32 v120, v120
	v_exp_f32_e32 v121, v121
	v_cvt_pk_bf16_f32 v114, v114, v115
	v_cvt_pk_bf16_f32 v115, v116, v117
	v_mfma_f32_16x16x32_bf16 v[166:169], v[130:133], v[98:101], v[166:169]
	v_cvt_pk_bf16_f32 v116, v118, v119
	v_cvt_pk_bf16_f32 v117, v120, v121
	s_waitcnt lgkmcnt(5)
	v_mfma_f32_32x32x16_bf16 v[82:97], v[238:241], v[142:145], 0
	v_exp_f32_e32 v106, v106
	v_exp_f32_e32 v107, v107
	v_exp_f32_e32 v108, v108
	ds_read_b128 v[238:241], v250 offset:13824
	v_mfma_f32_32x32x16_bf16 v[34:49], v[174:177], v[114:117], v[34:49]
	v_exp_f32_e32 v109, v109
	v_exp_f32_e32 v110, v110
	v_exp_f32_e32 v111, v111
	ds_read_b64_tr_b16 v[174:175], v252 offset:12288
	ds_read_b64_tr_b16 v[176:177], v252 offset:13824
	v_mfma_f32_32x32x16_bf16 v[50:65], v[178:181], v[114:117], v[50:65]
	v_exp_f32_e32 v112, v112
	v_exp_f32_e32 v113, v113
	v_cvt_pk_bf16_f32 v102, v106, v107
	v_cvt_pk_bf16_f32 v103, v108, v109
	ds_read_b64_tr_b16 v[178:179], v252 offset:12352
	ds_read_b64_tr_b16 v[180:181], v252 offset:13888
	v_mfma_f32_16x16x32_bf16 v[170:173], v[130:133], v[114:117], v[170:173]
	v_cvt_pk_bf16_f32 v104, v110, v111
	v_cvt_pk_bf16_f32 v105, v112, v113
	s_waitcnt lgkmcnt(5)
	v_mfma_f32_32x32x16_bf16 v[82:97], v[242:245], v[146:149], v[82:97]
	v_exp_f32_e32 v122, v122
	v_exp_f32_e32 v123, v123
	v_exp_f32_e32 v124, v124
	ds_read_b128 v[242:245], v250 offset:13856
	v_mfma_f32_32x32x16_bf16 v[2:17], v[182:185], v[102:105], v[2:17]
	v_exp_f32_e32 v125, v125
	v_exp_f32_e32 v126, v126
	v_exp_f32_e32 v127, v127
	v_mfma_f32_32x32x16_bf16 v[18:33], v[186:189], v[102:105], v[18:33]
	v_exp_f32_e32 v128, v128
	v_exp_f32_e32 v129, v129
	v_cvt_pk_bf16_f32 v118, v122, v123
	v_cvt_pk_bf16_f32 v119, v124, v125
	v_mfma_f32_16x16x32_bf16 v[166:169], v[130:133], v[102:105], v[166:169]
	v_cvt_pk_bf16_f32 v120, v126, v127
	v_cvt_pk_bf16_f32 v121, v128, v129
	s_waitcnt lgkmcnt(5)
	v_mfma_f32_32x32x16_bf16 v[98:113], v[238:241], v[134:137], 0
	v_exp_f32_e32 v66, v66
	v_exp_f32_e32 v67, v67
	v_exp_f32_e32 v68, v68
	ds_read_b128 v[238:241], v250 offset:13888
	v_mfma_f32_32x32x16_bf16 v[34:49], v[182:185], v[118:121], v[34:49]
	v_exp_f32_e32 v69, v69
	v_exp_f32_e32 v70, v70
	v_exp_f32_e32 v71, v71
	ds_read_b64_tr_b16 v[182:183], v252 offset:15360
	ds_read_b64_tr_b16 v[184:185], v252 offset:16896
	v_mfma_f32_32x32x16_bf16 v[50:65], v[186:189], v[118:121], v[50:65]
	v_exp_f32_e32 v72, v72
	v_exp_f32_e32 v73, v73
	v_cvt_pk_bf16_f32 v66, v66, v67
	v_cvt_pk_bf16_f32 v67, v68, v69
	ds_read_b64_tr_b16 v[186:187], v252 offset:15424
	ds_read_b64_tr_b16 v[188:189], v252 offset:16960
	v_mfma_f32_16x16x32_bf16 v[170:173], v[130:133], v[118:121], v[170:173]
	v_cvt_pk_bf16_f32 v68, v70, v71
	v_cvt_pk_bf16_f32 v69, v72, v73
	s_waitcnt lgkmcnt(5)
	v_mfma_f32_32x32x16_bf16 v[98:113], v[242:245], v[138:141], v[98:113]
	v_exp_f32_e32 v82, v82
	v_exp_f32_e32 v83, v83
	v_exp_f32_e32 v84, v84
	ds_read_b128 v[242:245], v250 offset:13920
	v_mfma_f32_32x32x16_bf16 v[2:17], v[174:177], v[66:69], v[2:17]
	v_exp_f32_e32 v85, v85
	v_exp_f32_e32 v86, v86
	v_exp_f32_e32 v87, v87
	v_mfma_f32_32x32x16_bf16 v[18:33], v[178:181], v[66:69], v[18:33]
	v_exp_f32_e32 v88, v88
	v_exp_f32_e32 v89, v89
	v_cvt_pk_bf16_f32 v82, v82, v83
	v_cvt_pk_bf16_f32 v83, v84, v85
	v_mfma_f32_16x16x32_bf16 v[166:169], v[130:133], v[66:69], v[166:169]
	v_cvt_pk_bf16_f32 v84, v86, v87
	v_cvt_pk_bf16_f32 v85, v88, v89
	s_barrier
	s_waitcnt lgkmcnt(5)
	v_mfma_f32_32x32x16_bf16 v[114:129], v[238:241], v[142:145], 0
	v_exp_f32_e32 v74, v74
	v_exp_f32_e32 v75, v75
	v_exp_f32_e32 v76, v76
	ds_read_b128 v[238:241], v251
	v_mfma_f32_32x32x16_bf16 v[34:49], v[174:177], v[82:85], v[34:49]
	v_exp_f32_e32 v77, v77
	v_exp_f32_e32 v78, v78
	v_exp_f32_e32 v79, v79
	ds_read_b64_tr_b16 v[174:175], v252 offset:18432
	ds_read_b64_tr_b16 v[176:177], v252 offset:19968
	v_mfma_f32_32x32x16_bf16 v[50:65], v[178:181], v[82:85], v[50:65]
	v_exp_f32_e32 v80, v80
	v_exp_f32_e32 v81, v81
	v_cvt_pk_bf16_f32 v70, v74, v75
	v_cvt_pk_bf16_f32 v71, v76, v77
	ds_read_b64_tr_b16 v[178:179], v252 offset:18496
	ds_read_b64_tr_b16 v[180:181], v252 offset:20032
	v_mfma_f32_16x16x32_bf16 v[170:173], v[130:133], v[82:85], v[170:173]
	v_cvt_pk_bf16_f32 v72, v78, v79
	v_cvt_pk_bf16_f32 v73, v80, v81
	s_waitcnt lgkmcnt(5)
	v_mfma_f32_32x32x16_bf16 v[114:129], v[242:245], v[146:149], v[114:129]
	v_exp_f32_e32 v90, v90
	v_exp_f32_e32 v91, v91
	v_exp_f32_e32 v92, v92
	ds_read_b128 v[242:245], v251 offset:32
	v_mfma_f32_32x32x16_bf16 v[2:17], v[182:185], v[70:73], v[2:17]
	v_exp_f32_e32 v93, v93
	v_exp_f32_e32 v94, v94
	v_exp_f32_e32 v95, v95
	v_mfma_f32_32x32x16_bf16 v[18:33], v[186:189], v[70:73], v[18:33]
	v_exp_f32_e32 v96, v96
	v_exp_f32_e32 v97, v97
	v_cvt_pk_bf16_f32 v86, v90, v91
	v_cvt_pk_bf16_f32 v87, v92, v93
	v_mfma_f32_16x16x32_bf16 v[166:169], v[130:133], v[70:73], v[166:169]
	v_cvt_pk_bf16_f32 v88, v94, v95
	v_cvt_pk_bf16_f32 v89, v96, v97
	s_waitcnt lgkmcnt(5)
	v_mfma_f32_32x32x16_bf16 v[66:81], v[238:241], v[134:137], 0
	v_exp_f32_e32 v98, v98
	v_exp_f32_e32 v99, v99
	v_exp_f32_e32 v100, v100
	ds_read_b128 v[238:241], v251 offset:64
	v_mfma_f32_32x32x16_bf16 v[34:49], v[182:185], v[86:89], v[34:49]
	v_exp_f32_e32 v101, v101
	v_exp_f32_e32 v102, v102
	v_exp_f32_e32 v103, v103
	ds_read_b64_tr_b16 v[182:183], v252 offset:21504
	ds_read_b64_tr_b16 v[184:185], v252 offset:23040
	v_mfma_f32_32x32x16_bf16 v[50:65], v[186:189], v[86:89], v[50:65]
	v_exp_f32_e32 v104, v104
	v_exp_f32_e32 v105, v105
	v_cvt_pk_bf16_f32 v98, v98, v99
	v_cvt_pk_bf16_f32 v99, v100, v101
	ds_read_b64_tr_b16 v[186:187], v252 offset:21568
	ds_read_b64_tr_b16 v[188:189], v252 offset:23104
	v_mfma_f32_16x16x32_bf16 v[170:173], v[130:133], v[86:89], v[170:173]
	v_cvt_pk_bf16_f32 v100, v102, v103
	v_cvt_pk_bf16_f32 v101, v104, v105
	s_waitcnt lgkmcnt(5)
	v_mfma_f32_32x32x16_bf16 v[66:81], v[242:245], v[138:141], v[66:81]
	v_exp_f32_e32 v114, v114
	v_exp_f32_e32 v115, v115
	v_exp_f32_e32 v116, v116
	ds_read_b128 v[242:245], v251 offset:96
	v_mfma_f32_32x32x16_bf16 v[2:17], v[174:177], v[98:101], v[2:17]
	v_exp_f32_e32 v117, v117
	v_exp_f32_e32 v118, v118
	v_exp_f32_e32 v119, v119
	v_mfma_f32_32x32x16_bf16 v[18:33], v[178:181], v[98:101], v[18:33]
	v_exp_f32_e32 v120, v120
	v_exp_f32_e32 v121, v121
	v_cvt_pk_bf16_f32 v114, v114, v115
	v_cvt_pk_bf16_f32 v115, v116, v117
	v_mfma_f32_16x16x32_bf16 v[166:169], v[130:133], v[98:101], v[166:169]
	v_cvt_pk_bf16_f32 v116, v118, v119
	v_cvt_pk_bf16_f32 v117, v120, v121
	s_waitcnt lgkmcnt(5)
	v_mfma_f32_32x32x16_bf16 v[82:97], v[238:241], v[142:145], 0
	v_exp_f32_e32 v106, v106
	v_exp_f32_e32 v107, v107
	v_exp_f32_e32 v108, v108
	ds_read_b128 v[238:241], v251 offset:4608
	v_mfma_f32_32x32x16_bf16 v[34:49], v[174:177], v[114:117], v[34:49]
	v_exp_f32_e32 v109, v109
	v_exp_f32_e32 v110, v110
	v_exp_f32_e32 v111, v111
	ds_read_b64_tr_b16 v[174:175], v215
	ds_read_b64_tr_b16 v[176:177], v215 offset:1536
	v_mfma_f32_32x32x16_bf16 v[50:65], v[178:181], v[114:117], v[50:65]
	v_exp_f32_e32 v112, v112
	v_exp_f32_e32 v113, v113
	v_cvt_pk_bf16_f32 v102, v106, v107
	v_cvt_pk_bf16_f32 v103, v108, v109
	ds_read_b64_tr_b16 v[178:179], v215 offset:64
	ds_read_b64_tr_b16 v[180:181], v215 offset:1600
	v_mfma_f32_16x16x32_bf16 v[170:173], v[130:133], v[114:117], v[170:173]
	v_cvt_pk_bf16_f32 v104, v110, v111
	v_cvt_pk_bf16_f32 v105, v112, v113
	s_waitcnt lgkmcnt(5)
	v_mfma_f32_32x32x16_bf16 v[82:97], v[242:245], v[146:149], v[82:97]
	v_exp_f32_e32 v122, v122
	v_exp_f32_e32 v123, v123
	v_exp_f32_e32 v124, v124
	ds_read_b128 v[242:245], v251 offset:4640
	v_mfma_f32_32x32x16_bf16 v[2:17], v[182:185], v[102:105], v[2:17]
	v_exp_f32_e32 v125, v125
	v_exp_f32_e32 v126, v126
	v_exp_f32_e32 v127, v127
	v_mfma_f32_32x32x16_bf16 v[18:33], v[186:189], v[102:105], v[18:33]
	v_exp_f32_e32 v128, v128
	v_exp_f32_e32 v129, v129
	v_cvt_pk_bf16_f32 v118, v122, v123
	v_cvt_pk_bf16_f32 v119, v124, v125
	v_mfma_f32_16x16x32_bf16 v[166:169], v[130:133], v[102:105], v[166:169]
	v_cvt_pk_bf16_f32 v120, v126, v127
	v_cvt_pk_bf16_f32 v121, v128, v129
	s_cmp_lg_u32 s14, s10
	s_cbranch_scc1 .Latt_loop
	s_waitcnt lgkmcnt(0)
	s_nop 1
	v_mfma_f32_16x16x32_bf16 v[170:173], v[130:133], v[118:121], v[170:173]
	v_mfma_f32_32x32x16_bf16 v[34:49], v[182:185], v[118:121], v[34:49]
	v_mfma_f32_32x32x16_bf16 v[50:65], v[186:189], v[118:121], v[50:65]
	s_nop 11
	global_load_dwordx4 v[98:101], v[212:213], off offset:32
	global_load_dwordx4 v[102:105], v[212:213], off offset:64
	global_load_dwordx4 v[106:109], v[212:213], off offset:96
	global_load_dwordx4 v[110:113], v[212:213], off offset:128
	global_load_dwordx4 v[114:117], v[212:213], off offset:160
	global_load_dwordx4 v[122:125], v[212:213], off offset:192
	global_load_dwordx4 v[126:129], v[212:213], off offset:224
	ds_bpermute_b32 v66, v237, v166
	s_nop 3
	ds_bpermute_b32 v67, v237, v170
	s_lshl_b32 s64, s9, 1
	v_mov_b32_e32 v215, v191
	s_mov_b32 s2, 0xf226000
	s_waitcnt lgkmcnt(1)
	v_div_scale_f32 v68, s[10:11], v66, v66, 1.0
	v_rcp_f32_e32 v69, v68
	s_add_i32 s8, s8, 1
	s_cmp_eq_u32 s8, s7
	v_fma_f32 v70, -v68, v69, 1.0
	v_fmac_f32_e32 v69, v70, v69
	v_div_scale_f32 v70, vcc, 1.0, v66, 1.0
	v_mul_f32_e32 v71, v70, v69
	v_fma_f32 v72, -v68, v71, v70
	v_fmac_f32_e32 v71, v72, v69
	v_fma_f32 v68, -v68, v71, v70
	v_div_fmas_f32 v68, v68, v69, v71
	v_div_fixup_f32 v66, v68, v66, 1.0
	s_waitcnt lgkmcnt(0)
	v_div_scale_f32 v68, s[10:11], v67, v67, v230
	v_rcp_f32_e32 v69, v68
	s_mov_b64 s[10:11], 0xf226400
	v_fma_f32 v70, -v68, v69, 1.0
	v_fmac_f32_e32 v69, v70, v69
	v_div_scale_f32 v70, vcc, v230, v67, v230
	v_mul_f32_e32 v71, v70, v69
	v_fma_f32 v72, -v68, v71, v70
	v_fmac_f32_e32 v71, v72, v69
	v_fma_f32 v68, -v68, v71, v70
	v_div_fmas_f32 v68, v68, v69, v71
	v_div_fixup_f32 v68, v68, v67, v230
	v_pk_mul_f32 v[62:63], v[62:63], v[68:69] op_sel_hi:[1,0]
	v_pk_mul_f32 v[34:35], v[34:35], v[68:69] op_sel_hi:[1,0]
	v_pk_fma_f32 v[30:31], v[30:31], v[66:67], v[62:63] op_sel_hi:[1,0,1] neg_lo:[0,0,1] neg_hi:[0,0,1]
	v_pk_mul_f32 v[62:63], v[64:65], v[68:69] op_sel_hi:[1,0]
	v_pk_mul_f32 v[36:37], v[36:37], v[68:69] op_sel_hi:[1,0]
	v_pk_fma_f32 v[32:33], v[32:33], v[66:67], v[62:63] op_sel_hi:[1,0,1] neg_lo:[0,0,1] neg_hi:[0,0,1]
	v_lshlrev_b64 v[62:63], 11, v[216:217]
	v_lshl_add_u64 v[62:63], s[54:55], 0, v[62:63]
	v_lshl_add_u64 v[74:75], v[62:63], 0, s[64:65]
	global_load_dwordx4 v[62:65], v[212:213], off
	v_pk_fma_f32 v[34:35], v[2:3], v[66:67], v[34:35] op_sel_hi:[1,0,1] neg_lo:[0,0,1] neg_hi:[0,0,1]
	v_pk_fma_f32 v[4:5], v[4:5], v[66:67], v[36:37] op_sel_hi:[1,0,1] neg_lo:[0,0,1] neg_hi:[0,0,1]
	v_pk_mul_f32 v[76:77], v[34:35], v[34:35]
	v_pk_mul_f32 v[40:41], v[40:41], v[68:69] op_sel_hi:[1,0]
	v_pk_mul_f32 v[38:39], v[38:39], v[68:69] op_sel_hi:[1,0]
	v_pk_mul_f32 v[44:45], v[44:45], v[68:69] op_sel_hi:[1,0]
	v_pk_mul_f32 v[42:43], v[42:43], v[68:69] op_sel_hi:[1,0]
	v_pk_mul_f32 v[48:49], v[48:49], v[68:69] op_sel_hi:[1,0]
	v_pk_mul_f32 v[46:47], v[46:47], v[68:69] op_sel_hi:[1,0]
	v_pk_mul_f32 v[52:53], v[52:53], v[68:69] op_sel_hi:[1,0]
	v_pk_mul_f32 v[50:51], v[50:51], v[68:69] op_sel_hi:[1,0]
	v_pk_mul_f32 v[56:57], v[56:57], v[68:69] op_sel_hi:[1,0]
	v_pk_mul_f32 v[54:55], v[54:55], v[68:69] op_sel_hi:[1,0]
	v_pk_mul_f32 v[60:61], v[60:61], v[68:69] op_sel_hi:[1,0]
	v_pk_mul_f32 v[58:59], v[58:59], v[68:69] op_sel_hi:[1,0]
	v_pk_mul_f32 v[36:37], v[4:5], v[4:5]
	v_pk_fma_f32 v[8:9], v[8:9], v[66:67], v[40:41] op_sel_hi:[1,0,1] neg_lo:[0,0,1] neg_hi:[0,0,1]
	v_pk_fma_f32 v[38:39], v[6:7], v[66:67], v[38:39] op_sel_hi:[1,0,1] neg_lo:[0,0,1] neg_hi:[0,0,1]
	v_pk_fma_f32 v[12:13], v[12:13], v[66:67], v[44:45] op_sel_hi:[1,0,1] neg_lo:[0,0,1] neg_hi:[0,0,1]
	v_pk_fma_f32 v[10:11], v[10:11], v[66:67], v[42:43] op_sel_hi:[1,0,1] neg_lo:[0,0,1] neg_hi:[0,0,1]
	v_pk_fma_f32 v[16:17], v[16:17], v[66:67], v[48:49] op_sel_hi:[1,0,1] neg_lo:[0,0,1] neg_hi:[0,0,1]
	v_pk_fma_f32 v[14:15], v[14:15], v[66:67], v[46:47] op_sel_hi:[1,0,1] neg_lo:[0,0,1] neg_hi:[0,0,1]
	v_pk_fma_f32 v[20:21], v[20:21], v[66:67], v[52:53] op_sel_hi:[1,0,1] neg_lo:[0,0,1] neg_hi:[0,0,1]
	v_pk_fma_f32 v[18:19], v[18:19], v[66:67], v[50:51] op_sel_hi:[1,0,1] neg_lo:[0,0,1] neg_hi:[0,0,1]
	v_pk_fma_f32 v[24:25], v[24:25], v[66:67], v[56:57] op_sel_hi:[1,0,1] neg_lo:[0,0,1] neg_hi:[0,0,1]
	v_pk_fma_f32 v[22:23], v[22:23], v[66:67], v[54:55] op_sel_hi:[1,0,1] neg_lo:[0,0,1] neg_hi:[0,0,1]
	v_pk_fma_f32 v[28:29], v[28:29], v[66:67], v[60:61] op_sel_hi:[1,0,1] neg_lo:[0,0,1] neg_hi:[0,0,1]
	v_pk_fma_f32 v[26:27], v[26:27], v[66:67], v[58:59] op_sel_hi:[1,0,1] neg_lo:[0,0,1] neg_hi:[0,0,1]
	v_add_f32_e32 v66, v76, v77
	v_add_f32_e32 v36, v36, v66
	v_pk_mul_f32 v[6:7], v[38:39], v[38:39]
	v_add_f32_e32 v36, v37, v36
	v_add_f32_e32 v6, v6, v36
	v_pk_mul_f32 v[40:41], v[8:9], v[8:9]
	v_add_f32_e32 v6, v7, v6
	v_add_f32_e32 v6, v40, v6
	v_pk_mul_f32 v[42:43], v[10:11], v[10:11]
	v_add_f32_e32 v6, v41, v6
	v_add_f32_e32 v6, v42, v6
	v_pk_mul_f32 v[44:45], v[12:13], v[12:13]
	v_add_f32_e32 v6, v43, v6
	v_add_f32_e32 v6, v44, v6
	v_pk_mul_f32 v[46:47], v[14:15], v[14:15]
	v_add_f32_e32 v6, v45, v6
	v_add_f32_e32 v6, v46, v6
	v_pk_mul_f32 v[48:49], v[16:17], v[16:17]
	v_add_f32_e32 v6, v47, v6
	v_add_f32_e32 v6, v48, v6
	v_pk_mul_f32 v[50:51], v[18:19], v[18:19]
	v_add_f32_e32 v6, v49, v6
	v_add_f32_e32 v6, v50, v6
	v_pk_mul_f32 v[52:53], v[20:21], v[20:21]
	v_add_f32_e32 v6, v51, v6
	v_add_f32_e32 v6, v52, v6
	v_pk_mul_f32 v[54:55], v[22:23], v[22:23]
	v_add_f32_e32 v6, v53, v6
	v_add_f32_e32 v6, v54, v6
	v_pk_mul_f32 v[56:57], v[24:25], v[24:25]
	v_add_f32_e32 v6, v55, v6
	v_add_f32_e32 v6, v56, v6
	v_pk_mul_f32 v[58:59], v[26:27], v[26:27]
	v_add_f32_e32 v6, v57, v6
	v_add_f32_e32 v6, v58, v6
	v_pk_mul_f32 v[60:61], v[28:29], v[28:29]
	v_add_f32_e32 v6, v59, v6
	v_add_f32_e32 v6, v60, v6
	v_pk_mul_f32 v[70:71], v[30:31], v[30:31]
	v_add_f32_e32 v6, v61, v6
	v_add_f32_e32 v6, v70, v6
	v_pk_mul_f32 v[72:73], v[32:33], v[32:33]
	v_add_f32_e32 v6, v71, v6
	v_add_f32_e32 v6, v72, v6
	v_add_f32_e32 v6, v73, v6
	ds_bpermute_b32 v7, v229, v6
	v_lshl_add_u64 v[74:75], v[74:75], 0, v[214:215]
	v_lshl_add_u64 v[2:3], v[74:75], 0, s[10:11]
	s_waitcnt lgkmcnt(0)
	v_add_f32_e32 v6, v6, v7
	v_fmamk_f32 v6, v6, 0x3c800000, v192
	v_cmp_gt_f32_e32 vcc, s70, v6
	v_mul_f32_e32 v7, 0x4b800000, v6
	s_nop 0
	v_cndmask_b32_e32 v6, v6, v7, vcc
	v_rsq_f32_e32 v6, v6
	s_nop 0
	v_mul_f32_e32 v7, 0x45800000, v6
	v_cndmask_b32_e32 v6, v6, v7, vcc
	v_mul_f32_e32 v36, v233, v6
	v_pk_mul_f32 v[6:7], v[34:35], v[36:37] op_sel_hi:[1,0]
	v_pk_mul_f32 v[4:5], v[4:5], v[36:37] op_sel_hi:[1,0]
	s_waitcnt vmcnt(0)
	v_pk_mul_f32 v[6:7], v[62:63], v[6:7]
	v_pk_mul_f32 v[4:5], v[64:65], v[4:5]
	v_cvt_pk_bf16_f32 v6, v6, v7
	v_cvt_pk_bf16_f32 v7, v4, v5
	v_add_co_u32_e32 v4, vcc, s2, v74
	v_pk_mul_f32 v[34:35], v[38:39], v[36:37] op_sel_hi:[1,0]
	s_nop 0
	v_addc_co_u32_e32 v5, vcc, 0, v75, vcc
	global_store_dwordx2 v[4:5], v[6:7], off offset:1024
	v_pk_mul_f32 v[8:9], v[8:9], v[36:37] op_sel_hi:[1,0]
	v_mov_b64_e32 v[4:5], v[98:99]
	v_mov_b64_e32 v[6:7], v[100:101]
	v_pk_mul_f32 v[4:5], v[4:5], v[34:35]
	v_pk_mul_f32 v[6:7], v[6:7], v[8:9]
	v_cvt_pk_bf16_f32 v4, v4, v5
	v_cvt_pk_bf16_f32 v5, v6, v7
	global_store_dwordx2 v[2:3], v[4:5], off offset:16
	v_pk_mul_f32 v[8:9], v[10:11], v[36:37] op_sel_hi:[1,0]
	v_mov_b64_e32 v[4:5], v[102:103]
	v_mov_b64_e32 v[6:7], v[104:105]
	v_pk_mul_f32 v[4:5], v[4:5], v[8:9]
	v_pk_mul_f32 v[8:9], v[12:13], v[36:37] op_sel_hi:[1,0]
	v_cvt_pk_bf16_f32 v4, v4, v5
	v_pk_mul_f32 v[6:7], v[6:7], v[8:9]
	v_pk_mul_f32 v[8:9], v[14:15], v[36:37] op_sel_hi:[1,0]
	v_cvt_pk_bf16_f32 v5, v6, v7
	global_store_dwordx2 v[2:3], v[4:5], off offset:32
	v_mov_b64_e32 v[4:5], v[106:107]
	v_mov_b64_e32 v[6:7], v[108:109]
	v_pk_mul_f32 v[4:5], v[4:5], v[8:9]
	v_pk_mul_f32 v[8:9], v[16:17], v[36:37] op_sel_hi:[1,0]
	v_cvt_pk_bf16_f32 v4, v4, v5
	v_pk_mul_f32 v[6:7], v[6:7], v[8:9]
	v_pk_mul_f32 v[8:9], v[18:19], v[36:37] op_sel_hi:[1,0]
	v_cvt_pk_bf16_f32 v5, v6, v7
	global_store_dwordx2 v[2:3], v[4:5], off offset:48
	v_mov_b64_e32 v[4:5], v[110:111]
	v_mov_b64_e32 v[6:7], v[112:113]
	v_pk_mul_f32 v[4:5], v[4:5], v[8:9]
	v_pk_mul_f32 v[8:9], v[20:21], v[36:37] op_sel_hi:[1,0]
	v_cvt_pk_bf16_f32 v4, v4, v5
	v_pk_mul_f32 v[6:7], v[6:7], v[8:9]
	v_pk_mul_f32 v[8:9], v[22:23], v[36:37] op_sel_hi:[1,0]
	v_cvt_pk_bf16_f32 v5, v6, v7
	global_store_dwordx2 v[2:3], v[4:5], off offset:64
	v_mov_b64_e32 v[4:5], v[114:115]
	v_mov_b64_e32 v[6:7], v[116:117]
	v_pk_mul_f32 v[4:5], v[4:5], v[8:9]
	v_pk_mul_f32 v[8:9], v[24:25], v[36:37] op_sel_hi:[1,0]
	v_cvt_pk_bf16_f32 v4, v4, v5
	v_pk_mul_f32 v[6:7], v[6:7], v[8:9]
	v_pk_mul_f32 v[8:9], v[26:27], v[36:37] op_sel_hi:[1,0]
	v_cvt_pk_bf16_f32 v5, v6, v7
	global_store_dwordx2 v[2:3], v[4:5], off offset:80
	v_mov_b64_e32 v[4:5], v[122:123]
	v_mov_b64_e32 v[6:7], v[124:125]
	v_pk_mul_f32 v[4:5], v[4:5], v[8:9]
	v_pk_mul_f32 v[8:9], v[28:29], v[36:37] op_sel_hi:[1,0]
	v_cvt_pk_bf16_f32 v4, v4, v5
	v_pk_mul_f32 v[6:7], v[6:7], v[8:9]
	v_pk_mul_f32 v[8:9], v[30:31], v[36:37] op_sel_hi:[1,0]
	v_cvt_pk_bf16_f32 v5, v6, v7
	global_store_dwordx2 v[2:3], v[4:5], off offset:96
	v_mov_b64_e32 v[4:5], v[126:127]
	v_mov_b64_e32 v[6:7], v[128:129]
	v_pk_mul_f32 v[4:5], v[4:5], v[8:9]
	v_pk_mul_f32 v[8:9], v[32:33], v[36:37] op_sel_hi:[1,0]
	v_cvt_pk_bf16_f32 v4, v4, v5
	v_pk_mul_f32 v[6:7], v[6:7], v[8:9]
	s_nop 0
	v_cvt_pk_bf16_f32 v5, v6, v7
	global_store_dwordx2 v[2:3], v[4:5], off offset:112
	s_cbranch_scc0 .LBB0_745
